# grid barrier without the cross-XCD arrival counter: each XCD leader adds 1 to every XCC release word (16-lane atomic) after its write-back; released at (gen+1)*nx
# speedup vs baseline: 1.0155x; 1.0046x over previous
.LBB0_238:
	s_or_b64 exec, exec, s[16:17]
	v_cvt_f32_u32_e32 v4, v2
	buffer_inv sc1
	s_waitcnt vmcnt(0)
	v_readfirstlane_b32 s3, v3
	v_sub_u32_e32 v3, 0, v2
	v_rcp_iflag_f32_e32 v4, v4
	v_add_u32_e32 v5, s3, v1
	v_mul_f32_e32 v4, 0x4f7ffffe, v4
	v_cvt_u32_f32_e32 v4, v4
	v_mul_lo_u32 v1, v3, v4
	v_mul_hi_u32 v1, v4, v1
	v_add_u32_e32 v1, v4, v1
	v_mul_hi_u32 v1, v5, v1
	v_mul_lo_u32 v3, v1, v2
	v_sub_u32_e32 v3, v5, v3
	v_add_u32_e32 v4, 1, v1
	v_cmp_ge_u32_e32 vcc, v3, v2
	s_nop 1
	v_cndmask_b32_e32 v1, v1, v4, vcc
	v_sub_u32_e32 v4, v3, v2
	v_cndmask_b32_e32 v3, v3, v4, vcc
	v_add_u32_e32 v4, 1, v1
	v_cmp_ge_u32_e32 vcc, v3, v2
	v_add_u32_e32 v3, 1, v5
	s_nop 0
	v_cndmask_b32_e32 v1, v1, v4, vcc
	v_mul_lo_u32 v4, v2, v1
	v_add_u32_e32 v2, v4, v2
	v_mov_b32_e32 v6, v1
	v_cmp_ne_u32_e32 vcc, v3, v2
	s_and_saveexec_b64 s[14:15], vcc
	s_xor_b64 s[14:15], exec, s[14:15]
	s_cbranch_execz .LBB0_252
	s_waitcnt lgkmcnt(0)
	v_add_u32_e32 v7, 1, v6
	v_mul_lo_u32 v7, v7, v0
	v_mov_b32_e32 v0, 0x2000
	global_load_dword v0, v0, s[12:13] offset:1024 sc1
	s_add_u32 s18, s12, 0x2400
	s_addc_u32 s19, s13, 0
	s_waitcnt vmcnt(0)
	v_cmp_lt_u32_e32 vcc, v0, v7
	s_and_saveexec_b64 s[16:17], vcc
	s_cbranch_execz .LBB0_251
	s_mov_b32 s3, 1
	s_mov_b64 s[20:21], 0
	v_mov_b32_e32 v0, 0
	s_branch .LBB0_242

.LBB0_246:
	global_load_dword v2, v0, s[18:19] sc1
	s_add_i32 s3, s3, 1
	s_mov_b64 s[26:27], -1
	s_waitcnt vmcnt(0)
	v_cmp_ge_u32_e32 vcc, v2, v7
	s_orn2_b64 s[24:25], vcc, exec
	s_branch .LBB0_241

.LBB0_252:
	s_andn2_saveexec_b64 s[14:15], s[14:15]
	s_cbranch_execz .LBB0_272
	s_mov_b64 s[14:15], exec
	buffer_wbl2 sc1
	s_waitcnt lgkmcnt(0)
	s_waitcnt vmcnt(0)
	v_add_u32_e32 v5, 1, v6
	v_mul_lo_u32 v5, v5, v0
	s_mov_b64 s[98:99], exec
	s_mov_b64 exec, 0xffff
	v_mbcnt_lo_u32_b32 v2, -1, 0
	v_lshlrev_b32_e32 v2, 8, v2
	v_add_u32_e32 v2, 0x2400, v2
	v_mov_b32_e32 v3, 1
	global_atomic_add v2, v3, s[10:11]
	s_mov_b64 exec, s[98:99]
	s_add_u32 s16, s12, 0x2400
	s_addc_u32 s17, s13, 0
	s_mov_b64 s[18:19], 0
	v_mov_b64_e32 v[0:1], s[16:17]
	s_mov_b64 s[14:15], exec
	v_mov_b32_e32 v0, 0
	global_load_dword v1, v0, s[16:17] sc1
	s_mov_b64 s[22:23], 0
	s_waitcnt vmcnt(0)
	v_cmp_lt_u32_e32 vcc, v1, v5
	s_and_saveexec_b64 s[20:21], vcc
	s_cbranch_execz .LBB0_266
	s_add_u32 s18, s10, 0x200
	s_addc_u32 s19, s11, 0
	s_mov_b32 s3, 1
	s_mov_b64 s[10:11], 0
	s_branch .LBB0_259

.LBB0_269:
	s_or_b64 exec, exec, s[10:11]
	s_mov_b64 s[10:11], exec
	v_mbcnt_lo_u32_b32 v0, s10, 0
	v_mbcnt_hi_u32_b32 v0, s11, v0
	v_cmp_eq_u32_e32 vcc, 0, v0
	s_waitcnt vmcnt(0)
	s_and_saveexec_b64 s[14:15], vcc
	s_cbranch_execz .LBB0_271
	s_bcnt1_i32_b64 s3, s[10:11]
	v_mov_b32_e32 v0, 0x2000
	v_mov_b32_e32 v1, s3

.LBB0_514:
	s_or_b64 exec, exec, s[12:13]
	v_cvt_f32_u32_e32 v4, v2
	buffer_inv sc1
	s_waitcnt vmcnt(0)
	v_readfirstlane_b32 s3, v3
	v_sub_u32_e32 v3, 0, v2
	v_rcp_iflag_f32_e32 v4, v4
	v_add_u32_e32 v5, s3, v1
	v_mul_f32_e32 v4, 0x4f7ffffe, v4
	v_cvt_u32_f32_e32 v4, v4
	v_mul_lo_u32 v1, v3, v4
	v_mul_hi_u32 v1, v4, v1
	v_add_u32_e32 v1, v4, v1
	v_mul_hi_u32 v1, v5, v1
	v_mul_lo_u32 v3, v1, v2
	v_sub_u32_e32 v3, v5, v3
	v_add_u32_e32 v4, 1, v1
	v_cmp_ge_u32_e32 vcc, v3, v2
	s_nop 1
	v_cndmask_b32_e32 v1, v1, v4, vcc
	v_sub_u32_e32 v4, v3, v2
	v_cndmask_b32_e32 v3, v3, v4, vcc
	v_add_u32_e32 v4, 1, v1
	v_cmp_ge_u32_e32 vcc, v3, v2
	v_add_u32_e32 v3, 1, v5
	s_nop 0
	v_cndmask_b32_e32 v1, v1, v4, vcc
	v_mul_lo_u32 v4, v2, v1
	v_add_u32_e32 v2, v4, v2
	v_mov_b32_e32 v6, v1
	v_cmp_ne_u32_e32 vcc, v3, v2
	s_and_saveexec_b64 s[10:11], vcc
	s_xor_b64 s[10:11], exec, s[10:11]
	s_cbranch_execz .LBB0_528
	s_waitcnt lgkmcnt(0)
	v_add_u32_e32 v7, 1, v6
	v_mul_lo_u32 v7, v7, v0
	v_mov_b32_e32 v0, 0x2000
	global_load_dword v0, v0, s[8:9] offset:1024 sc1
	s_add_u32 s14, s8, 0x2400
	s_addc_u32 s15, s9, 0
	s_waitcnt vmcnt(0)
	v_cmp_lt_u32_e32 vcc, v0, v7
	s_and_saveexec_b64 s[12:13], vcc
	s_cbranch_execz .LBB0_527
	s_mov_b32 s3, 1
	s_mov_b64 s[16:17], 0
	v_mov_b32_e32 v0, 0
	s_branch .LBB0_518

.LBB0_522:
	global_load_dword v2, v0, s[14:15] sc1
	s_add_i32 s3, s3, 1
	s_mov_b64 s[22:23], -1
	s_waitcnt vmcnt(0)
	v_cmp_ge_u32_e32 vcc, v2, v7
	s_orn2_b64 s[20:21], vcc, exec
	s_branch .LBB0_517

.LBB0_528:
	s_andn2_saveexec_b64 s[10:11], s[10:11]
	s_cbranch_execz .LBB0_548
	s_mov_b64 s[10:11], exec
	buffer_wbl2 sc1
	s_waitcnt lgkmcnt(0)
	s_waitcnt vmcnt(0)
	v_add_u32_e32 v5, 1, v6
	v_mul_lo_u32 v5, v5, v0
	s_mov_b64 s[98:99], exec
	s_mov_b64 exec, 0xffff
	v_mbcnt_lo_u32_b32 v2, -1, 0
	v_lshlrev_b32_e32 v2, 8, v2
	v_add_u32_e32 v2, 0x2400, v2
	v_mov_b32_e32 v3, 1
	global_atomic_add v2, v3, s[6:7]
	s_mov_b64 exec, s[98:99]
	s_add_u32 s12, s8, 0x2400
	s_addc_u32 s13, s9, 0
	s_mov_b64 s[14:15], 0
	v_mov_b64_e32 v[0:1], s[12:13]
	s_mov_b64 s[10:11], exec
	v_mov_b32_e32 v0, 0
	global_load_dword v1, v0, s[12:13] sc1
	s_mov_b64 s[18:19], 0
	s_waitcnt vmcnt(0)
	v_cmp_lt_u32_e32 vcc, v1, v5
	s_and_saveexec_b64 s[16:17], vcc
	s_cbranch_execz .LBB0_542
	s_add_u32 s14, s6, 0x200
	s_addc_u32 s15, s7, 0
	s_mov_b32 s3, 1
	s_mov_b64 s[6:7], 0
	s_branch .LBB0_535

.LBB0_545:
	s_or_b64 exec, exec, s[6:7]
	s_mov_b64 s[6:7], exec
	v_mbcnt_lo_u32_b32 v0, s6, 0
	v_mbcnt_hi_u32_b32 v0, s7, v0
	v_cmp_eq_u32_e32 vcc, 0, v0
	s_waitcnt vmcnt(0)
	s_and_saveexec_b64 s[10:11], vcc
	s_cbranch_execz .LBB0_547
	s_bcnt1_i32_b64 s3, s[6:7]
	v_mov_b32_e32 v0, 0x2000
	v_mov_b32_e32 v1, s3
